# P0 x->bf16 row loop double-buffered: landed rows copied to free VGPRs and the next trip's 16 loads issued before this trip's 20 stores; top wait leaves the previous trip's stores outstanding
# baseline (speedup 1.0000x reference)
; __device__ __forceinline__ void p0_prologue(const Args& a, Frame& F) {
;     ...
;     for (int m0 = 4 * gw; m0 < MP; m0 += 4 * NGW) {
;         f32x4 v[4][4];
; #pragma unroll
;         for (int r = 0; r < 4; ++r) { const int m = m0 + r;
;             if (m < MP) { const f32x4* xr = (const f32x4*)(a.in[0] + (size_t)m * D) + F.lane;
; #pragma unroll
;                 for (int j = 0; j < 4; ++j) v[r][j] = __builtin_nontemporal_load(xr + 64 * j); } }
.LBB0_168:
	s_add_i32 s14, s14, s16
	s_add_i32 s9, s9, s38
	s_add_i32 s11, s11, s39
	v_lshl_add_u64 v[88:89], v[88:89], 0, s[18:19]
	s_cmpk_gt_i32 s14, 0x7fff
	v_lshl_add_u64 v[90:91], v[90:91], 0, s[20:21]
	s_cbranch_scc1 .LBB0_188
	s_mov_b64 s[28:29], s[50:51]
	s_mov_b64 s[26:27], s[52:53]
	s_mov_b64 s[22:23], s[54:55]
	s_branch .Lx_top
.LBB0_169:
	s_mov_b32 s99, 0
	v_add_co_u32_e32 v66, vcc, 0xffffd000, v90
	s_add_i32 s15, s14, 1
	s_waitcnt lgkmcnt(0)
	v_addc_co_u32_e32 v67, vcc, -1, v91, vcc
	global_load_dwordx4 v[78:81], v[66:67], off offset:-3072 nt
	global_load_dwordx4 v[74:77], v[66:67], off offset:-2048 nt
	global_load_dwordx4 v[70:73], v[66:67], off offset:-1024 nt
	s_nop 0
	global_load_dwordx4 v[66:69], v[66:67], off nt
	s_cmp_lt_i32 s15, 0x8000
	s_cselect_b64 s[28:29], -1, 0
	s_cmpk_gt_i32 s15, 0x7fff
	s_cbranch_scc1 .LBB0_171
	v_add_co_u32_e32 v50, vcc, 0xffffe000, v90
	s_nop 1
	v_addc_co_u32_e32 v51, vcc, -1, v91, vcc
	global_load_dwordx4 v[62:65], v[50:51], off offset:-3072 nt
	global_load_dwordx4 v[58:61], v[50:51], off offset:-2048 nt
	global_load_dwordx4 v[54:57], v[50:51], off offset:-1024 nt
	s_nop 0
	global_load_dwordx4 v[50:53], v[50:51], off nt

.LBB0_175:
.Lx_top:
	s_cmp_eq_u32 s99, 0
	s_cbranch_scc1 .Lx_w0
	s_waitcnt vmcnt(20)
	s_branch .Lx_w1

; __device__ __forceinline__ void p0_prologue(const Args& a, Frame& F) {
;     ...
;     for (int m0 = 4 * gw; m0 < MP; m0 += 4 * NGW) {
;         f32x4 v[4][4];
; #pragma unroll
;         for (int r = 0; r < 4; ++r) { const int m = m0 + r;
;             if (m < MP) { const f32x4* xr = (const f32x4*)(a.in[0] + (size_t)m * D) + F.lane;
; #pragma unroll
;                 for (int j = 0; j < 4; ++j) v[r][j] = __builtin_nontemporal_load(xr + 64 * j); } }
.Lx_w1:
	s_mov_b32 s99, 1
	v_mov_b64_e32 v[172:173], v[18:19]
	v_mov_b64_e32 v[174:175], v[20:21]
	v_mov_b64_e32 v[176:177], v[22:23]
	v_mov_b64_e32 v[178:179], v[24:25]
	v_mov_b64_e32 v[180:181], v[26:27]
	v_mov_b64_e32 v[182:183], v[28:29]
	v_mov_b64_e32 v[184:185], v[30:31]
	v_mov_b64_e32 v[186:187], v[32:33]
	v_mov_b64_e32 v[188:189], v[34:35]
	v_mov_b64_e32 v[190:191], v[36:37]
	v_mov_b64_e32 v[192:193], v[38:39]
	v_mov_b64_e32 v[194:195], v[40:41]
	v_mov_b64_e32 v[196:197], v[42:43]
	v_mov_b64_e32 v[198:199], v[44:45]
	v_mov_b64_e32 v[200:201], v[46:47]
	v_mov_b64_e32 v[202:203], v[48:49]
	v_mov_b64_e32 v[204:205], v[50:51]
	v_mov_b64_e32 v[206:207], v[52:53]
	v_mov_b64_e32 v[208:209], v[54:55]
	v_mov_b64_e32 v[210:211], v[56:57]
	v_mov_b64_e32 v[212:213], v[58:59]
	v_mov_b64_e32 v[214:215], v[60:61]
	v_mov_b64_e32 v[216:217], v[62:63]
	v_mov_b64_e32 v[218:219], v[64:65]
	v_mov_b64_e32 v[220:221], v[66:67]
	v_mov_b64_e32 v[222:223], v[68:69]
	v_mov_b64_e32 v[224:225], v[70:71]
	v_mov_b64_e32 v[226:227], v[72:73]
	v_mov_b64_e32 v[228:229], v[74:75]
	v_mov_b64_e32 v[230:231], v[76:77]
	v_mov_b64_e32 v[232:233], v[78:79]
	v_mov_b64_e32 v[234:235], v[80:81]
	v_lshl_add_u64 v[236:237], v[90:91], 0, s[20:21]
	s_add_i32 s98, s14, s16
	s_cmpk_gt_i32 s98, 0x7fff
	s_cbranch_scc1 .Lx_175
	v_add_co_u32_e32 v66, vcc, 0xffffd000, v236
	s_add_i32 s100, s98, 1
	s_waitcnt lgkmcnt(0)
	v_addc_co_u32_e32 v67, vcc, -1, v237, vcc
	global_load_dwordx4 v[78:81], v[66:67], off offset:-3072 nt
	global_load_dwordx4 v[74:77], v[66:67], off offset:-2048 nt
	global_load_dwordx4 v[70:73], v[66:67], off offset:-1024 nt
	s_nop 0
	global_load_dwordx4 v[66:69], v[66:67], off nt
	s_cmp_lt_i32 s100, 0x8000
	s_cselect_b64 s[50:51], -1, 0
	s_cmpk_gt_i32 s100, 0x7fff
	s_cbranch_scc1 .Lx_171
	v_add_co_u32_e32 v50, vcc, 0xffffe000, v236
	s_nop 1
	v_addc_co_u32_e32 v51, vcc, -1, v237, vcc
	global_load_dwordx4 v[62:65], v[50:51], off offset:-3072 nt
	global_load_dwordx4 v[58:61], v[50:51], off offset:-2048 nt
	global_load_dwordx4 v[54:57], v[50:51], off offset:-1024 nt
	s_nop 0
	global_load_dwordx4 v[50:53], v[50:51], off nt
.Lx_171:
	s_add_i32 s100, s98, 2
	s_cmp_lt_i32 s100, 0x8000
	s_cselect_b64 s[52:53], -1, 0
	s_cmpk_gt_i32 s100, 0x7fff
	s_cbranch_scc1 .Lx_173
	v_add_co_u32_e32 v34, vcc, 0xfffff000, v236
	s_nop 1
	v_addc_co_u32_e32 v35, vcc, -1, v237, vcc
	global_load_dwordx4 v[46:49], v[34:35], off offset:-3072 nt
	global_load_dwordx4 v[42:45], v[34:35], off offset:-2048 nt
	global_load_dwordx4 v[38:41], v[34:35], off offset:-1024 nt
	s_nop 0
	global_load_dwordx4 v[34:37], v[236:237], off offset:-4096 nt
.Lx_173:
	s_add_i32 s100, s98, 3
	s_cmp_lt_i32 s100, 0x8000
	s_cselect_b64 s[54:55], -1, 0
	s_cmpk_gt_i32 s100, 0x7fff
	s_cbranch_scc1 .Lx_175
	global_load_dwordx4 v[30:33], v[236:237], off offset:-3072 nt
	global_load_dwordx4 v[26:29], v[236:237], off offset:-2048 nt
	global_load_dwordx4 v[22:25], v[236:237], off offset:-1024 nt
	global_load_dwordx4 v[18:21], v[236:237], off nt
.Lx_175:
	v_mul_f32_e32 v83, v233, v233
	v_mul_f32_e32 v85, v235, v235
	v_fmac_f32_e32 v83, v232, v232
	v_fmac_f32_e32 v85, v234, v234
	v_add_f32_e32 v83, v83, v85
	v_mul_f32_e32 v85, v229, v229
	v_mul_f32_e32 v86, v231, v231
	v_fmac_f32_e32 v85, v228, v228
	v_fmac_f32_e32 v86, v230, v230
	v_add_f32_e32 v85, v85, v86
	v_add_f32_e32 v83, v83, v85
	v_mul_f32_e32 v85, v225, v225
	v_mul_f32_e32 v86, v227, v227
	v_fmac_f32_e32 v85, v224, v224
	v_fmac_f32_e32 v86, v226, v226
	v_add_f32_e32 v85, v85, v86
	v_add_f32_e32 v83, v83, v85
	v_mul_f32_e32 v85, v221, v221
	v_mul_f32_e32 v86, v223, v223
	v_fmac_f32_e32 v85, v220, v220
	v_fmac_f32_e32 v86, v222, v222
	v_add_f32_e32 v85, v85, v86
	v_add_f32_e32 v83, v83, v85
	ds_bpermute_b32 v85, v97, v83
	s_lshr_b32 s15, s14, 3
	s_and_b32 s17, s11, 0x4000
	v_cvt_pk_bf16_f32 v232, v232, v233
	v_cvt_pk_bf16_f32 v233, v234, v235
	s_waitcnt lgkmcnt(0)
	v_add_f32_e32 v83, v83, v85
	ds_bpermute_b32 v85, v98, v83
	v_cvt_pk_bf16_f32 v228, v228, v229
	v_cvt_pk_bf16_f32 v229, v230, v231
	v_cvt_pk_bf16_f32 v224, v224, v225
	v_cvt_pk_bf16_f32 v225, v226, v227
	s_waitcnt lgkmcnt(0)
	v_add_f32_e32 v83, v83, v85
	ds_bpermute_b32 v85, v99, v83
	v_cvt_pk_bf16_f32 v220, v220, v221
	v_cvt_pk_bf16_f32 v221, v222, v223
	s_waitcnt lgkmcnt(0)
	v_add_f32_e32 v85, v83, v85
	ds_bpermute_b32 v86, v100, v85
	v_and_or_b32 v83, s15, 14, v103
	s_ashr_i32 s15, s14, 4
	s_add_u32 s24, s34, s17
	s_addc_u32 s25, s35, 0
	s_waitcnt lgkmcnt(0)
	v_add_f32_e32 v85, v85, v86
	ds_bpermute_b32 v86, v101, v85
	s_and_b32 s17, s9, 0x300
	v_lshlrev_b32_e32 v83, 10, v83
	v_and_or_b32 v110, s15, -16, v96
	v_ashrrev_i32_e32 v111, 31, v110
	s_waitcnt lgkmcnt(0)
	v_add_f32_e32 v85, v85, v86
	v_or_b32_e32 v86, s17, v105
	s_lshr_b32 s17, s9, 4
	s_and_b32 s17, s17, 32
	v_bitop3_b32 v86, v86, v83, s17 bitop3:0xde
	v_lshl_add_u64 v[108:109], s[24:25], 0, v[86:87]
	v_lshlrev_b64 v[92:93], 15, v[110:111]
	v_lshl_add_u64 v[112:113], v[108:109], 0, v[92:93]
	global_store_dwordx2 v[112:113], v[232:233], off
	v_or_b32_e32 v232, 4, v110
	v_ashrrev_i32_e32 v233, 31, v232
	v_lshlrev_b64 v[232:233], 15, v[232:233]
	v_lshl_add_u64 v[234:235], v[108:109], 0, v[232:233]
	global_store_dwordx2 v[234:235], v[228:229], off
	v_or_b32_e32 v228, 8, v110
	v_ashrrev_i32_e32 v229, 31, v228
	v_lshlrev_b64 v[228:229], 15, v[228:229]
	ds_bpermute_b32 v106, v102, v85
	v_lshl_add_u64 v[230:231], v[108:109], 0, v[228:229]
	global_store_dwordx2 v[230:231], v[224:225], off
	v_or_b32_e32 v224, 12, v110
	v_ashrrev_i32_e32 v225, 31, v224
	v_lshlrev_b64 v[224:225], 15, v[224:225]
	v_lshl_add_u64 v[226:227], v[108:109], 0, v[224:225]
	global_store_dwordx2 v[226:227], v[220:221], off
	s_and_saveexec_b64 s[30:31], s[4:5]
	s_cbranch_execz .LBB0_181
	s_waitcnt lgkmcnt(0)
	v_add_f32_e32 v220, v85, v106
	v_cndmask_b32_e64 v220, 0, v220, s[6:7]
	global_store_dword v[88:89], v220, off offset:-192
	s_or_b64 exec, exec, s[30:31]
	s_andn2_b64 vcc, exec, s[28:29]
	s_cbranch_vccz .LBB0_182

.LBB0_178:
	v_mul_f32_e32 v220, v201, v201
	s_waitcnt lgkmcnt(0)
	v_mul_f32_e32 v221, v203, v203
	v_fmac_f32_e32 v220, v200, v200
	v_fmac_f32_e32 v221, v202, v202
	v_add_f32_e32 v220, v220, v221
	v_mul_f32_e32 v221, v197, v197
	v_mul_f32_e32 v222, v199, v199
	v_fmac_f32_e32 v221, v196, v196
	v_fmac_f32_e32 v222, v198, v198
	v_add_f32_e32 v221, v221, v222
	v_add_f32_e32 v220, v221, v220
	v_mul_f32_e32 v221, v193, v193
	v_mul_f32_e32 v222, v195, v195
	v_fmac_f32_e32 v221, v192, v192
	v_fmac_f32_e32 v222, v194, v194
	v_add_f32_e32 v221, v221, v222
	v_add_f32_e32 v220, v221, v220
	v_mul_f32_e32 v221, v189, v189
	v_mul_f32_e32 v222, v191, v191
	v_fmac_f32_e32 v221, v188, v188
	v_fmac_f32_e32 v222, v190, v190
	v_add_f32_e32 v221, v221, v222
	v_add_f32_e32 v220, v221, v220
	ds_bpermute_b32 v221, v97, v220
	s_add_i32 s15, s9, 0x80
	s_and_b32 s17, s15, 0x380
	s_lshr_b32 s15, s15, 4
	v_or_b32_e32 v222, s17, v105
	s_waitcnt lgkmcnt(0)
	v_add_f32_e32 v220, v220, v221
	ds_bpermute_b32 v221, v98, v220
	s_and_b32 s15, s15, 32
	v_bitop3_b32 v86, v222, v83, s15 bitop3:0xde
	v_lshl_add_u64 v[222:223], s[24:25], 0, v[86:87]
	v_lshl_add_u64 v[226:227], v[222:223], 0, v[92:93]
	s_waitcnt lgkmcnt(0)
	v_add_f32_e32 v220, v220, v221
	ds_bpermute_b32 v221, v99, v220
	v_cvt_pk_bf16_f32 v230, v200, v201
	v_cvt_pk_bf16_f32 v231, v202, v203
	global_store_dwordx2 v[226:227], v[230:231], off
	v_lshl_add_u64 v[226:227], v[222:223], 0, v[232:233]
	s_waitcnt lgkmcnt(0)
	v_add_f32_e32 v220, v220, v221
	ds_bpermute_b32 v221, v100, v220
	v_cvt_pk_bf16_f32 v230, v196, v197
	v_cvt_pk_bf16_f32 v231, v198, v199
	global_store_dwordx2 v[226:227], v[230:231], off
	v_lshl_add_u64 v[226:227], v[222:223], 0, v[228:229]
	s_waitcnt lgkmcnt(0)
	v_add_f32_e32 v220, v220, v221
	ds_bpermute_b32 v221, v101, v220
	v_cvt_pk_bf16_f32 v230, v192, v193
	v_cvt_pk_bf16_f32 v231, v194, v195
	global_store_dwordx2 v[226:227], v[230:231], off
	v_lshl_add_u64 v[222:223], v[222:223], 0, v[224:225]
	s_waitcnt lgkmcnt(0)
	v_add_f32_e32 v220, v220, v221
	ds_bpermute_b32 v221, v102, v220
	v_cvt_pk_bf16_f32 v226, v188, v189
	v_cvt_pk_bf16_f32 v227, v190, v191
	global_store_dwordx2 v[222:223], v[226:227], off
	s_and_saveexec_b64 s[26:27], s[4:5]
	s_cbranch_execz .LBB0_180
	s_waitcnt lgkmcnt(0)
	v_add_f32_e32 v220, v220, v221
	v_cndmask_b32_e64 v220, 0, v220, s[6:7]
	global_store_dword v[88:89], v220, off offset:-64

.LBB0_182:
	v_mul_f32_e32 v220, v217, v217
	v_mul_f32_e32 v221, v219, v219
	v_fmac_f32_e32 v220, v216, v216
	v_fmac_f32_e32 v221, v218, v218
	v_add_f32_e32 v220, v220, v221
	v_mul_f32_e32 v221, v213, v213
	v_mul_f32_e32 v222, v215, v215
	v_fmac_f32_e32 v221, v212, v212
	v_fmac_f32_e32 v222, v214, v214
	v_add_f32_e32 v221, v221, v222
	v_add_f32_e32 v220, v221, v220
	v_mul_f32_e32 v221, v209, v209
	v_mul_f32_e32 v222, v211, v211
	v_fmac_f32_e32 v221, v208, v208
	v_fmac_f32_e32 v222, v210, v210
	v_add_f32_e32 v221, v221, v222
	v_add_f32_e32 v220, v221, v220
	v_mul_f32_e32 v221, v205, v205
	v_mul_f32_e32 v222, v207, v207
	v_fmac_f32_e32 v221, v204, v204
	v_fmac_f32_e32 v222, v206, v206
	v_add_f32_e32 v221, v221, v222
	v_add_f32_e32 v220, v221, v220
	ds_bpermute_b32 v221, v97, v220
	s_add_i32 s15, s9, 64
	s_and_b32 s17, s15, 0x340
	s_lshr_b32 s15, s15, 4
	v_or_b32_e32 v222, s17, v104
	s_waitcnt lgkmcnt(0)
	v_add_f32_e32 v220, v220, v221
	ds_bpermute_b32 v221, v98, v220
	s_and_b32 s15, s15, 32
	v_bitop3_b32 v86, v222, v83, s15 bitop3:0xde
	v_lshl_add_u64 v[222:223], s[24:25], 0, v[86:87]
	v_lshl_add_u64 v[226:227], v[222:223], 0, v[92:93]
	s_waitcnt lgkmcnt(0)
	v_add_f32_e32 v220, v220, v221
	ds_bpermute_b32 v221, v99, v220
	v_cvt_pk_bf16_f32 v230, v216, v217
	v_cvt_pk_bf16_f32 v231, v218, v219
	global_store_dwordx2 v[226:227], v[230:231], off
	v_lshl_add_u64 v[226:227], v[222:223], 0, v[232:233]
	s_waitcnt lgkmcnt(0)
	v_add_f32_e32 v220, v220, v221
	ds_bpermute_b32 v221, v100, v220
	v_cvt_pk_bf16_f32 v230, v212, v213
	v_cvt_pk_bf16_f32 v231, v214, v215
	global_store_dwordx2 v[226:227], v[230:231], off
	v_lshl_add_u64 v[226:227], v[222:223], 0, v[228:229]
	s_waitcnt lgkmcnt(0)
	v_add_f32_e32 v220, v220, v221
	ds_bpermute_b32 v221, v101, v220
	v_cvt_pk_bf16_f32 v230, v208, v209
	v_cvt_pk_bf16_f32 v231, v210, v211
	global_store_dwordx2 v[226:227], v[230:231], off
	v_lshl_add_u64 v[222:223], v[222:223], 0, v[224:225]
	s_waitcnt lgkmcnt(0)
	v_add_f32_e32 v220, v220, v221
	ds_bpermute_b32 v221, v102, v220
	v_cvt_pk_bf16_f32 v226, v204, v205
	v_cvt_pk_bf16_f32 v227, v206, v207
	global_store_dwordx2 v[222:223], v[226:227], off
	s_and_saveexec_b64 s[28:29], s[4:5]
	s_cbranch_execz .LBB0_184
	s_waitcnt lgkmcnt(0)
	v_add_f32_e32 v220, v220, v221
	v_cndmask_b32_e64 v220, 0, v220, s[6:7]
	global_store_dword v[88:89], v220, off offset:-128

.LBB0_186:
	v_mul_f32_e32 v220, v185, v185
	s_waitcnt lgkmcnt(0)
	v_mul_f32_e32 v221, v187, v187
	v_fmac_f32_e32 v220, v184, v184
	v_fmac_f32_e32 v221, v186, v186
	v_add_f32_e32 v220, v220, v221
	v_mul_f32_e32 v221, v181, v181
	v_mul_f32_e32 v222, v183, v183
	v_fmac_f32_e32 v221, v180, v180
	v_fmac_f32_e32 v222, v182, v182
	v_add_f32_e32 v221, v221, v222
	v_add_f32_e32 v220, v221, v220
	v_mul_f32_e32 v221, v177, v177
	v_mul_f32_e32 v222, v179, v179
	v_fmac_f32_e32 v221, v176, v176
	v_fmac_f32_e32 v222, v178, v178
	v_add_f32_e32 v221, v221, v222
	v_add_f32_e32 v220, v221, v220
	v_mul_f32_e32 v221, v173, v173
	v_mul_f32_e32 v222, v175, v175
	v_fmac_f32_e32 v221, v172, v172
	v_fmac_f32_e32 v222, v174, v174
	v_add_f32_e32 v221, v221, v222
	v_add_f32_e32 v220, v221, v220
	ds_bpermute_b32 v221, v97, v220
	s_add_i32 s15, s9, 0xc0
	s_and_b32 s17, s15, 0x3c0
	s_lshr_b32 s15, s15, 4
	v_or_b32_e32 v222, s17, v104
	s_waitcnt lgkmcnt(0)
	v_add_f32_e32 v220, v220, v221
	ds_bpermute_b32 v221, v98, v220
	s_and_b32 s15, s15, 32
	v_bitop3_b32 v86, v222, v83, s15 bitop3:0xde
	v_lshl_add_u64 v[222:223], s[24:25], 0, v[86:87]
	v_lshl_add_u64 v[226:227], v[222:223], 0, v[92:93]
	s_waitcnt lgkmcnt(0)
	v_add_f32_e32 v220, v220, v221
	ds_bpermute_b32 v221, v99, v220
	v_cvt_pk_bf16_f32 v230, v184, v185
	v_cvt_pk_bf16_f32 v231, v186, v187
	global_store_dwordx2 v[226:227], v[230:231], off
	v_lshl_add_u64 v[226:227], v[222:223], 0, v[232:233]
	s_waitcnt lgkmcnt(0)
	v_add_f32_e32 v220, v220, v221
	ds_bpermute_b32 v221, v100, v220
	v_cvt_pk_bf16_f32 v230, v180, v181
	v_cvt_pk_bf16_f32 v231, v182, v183
	global_store_dwordx2 v[226:227], v[230:231], off
	v_lshl_add_u64 v[226:227], v[222:223], 0, v[228:229]
	s_waitcnt lgkmcnt(0)
	v_add_f32_e32 v220, v220, v221
	ds_bpermute_b32 v221, v101, v220
	v_cvt_pk_bf16_f32 v228, v176, v177
	v_cvt_pk_bf16_f32 v229, v178, v179
	v_lshl_add_u64 v[222:223], v[222:223], 0, v[224:225]
	v_cvt_pk_bf16_f32 v224, v172, v173
	s_waitcnt lgkmcnt(0)
	v_add_f32_e32 v220, v220, v221
	ds_bpermute_b32 v221, v102, v220
	v_cvt_pk_bf16_f32 v225, v174, v175
	global_store_dwordx2 v[226:227], v[228:229], off
	global_store_dwordx2 v[222:223], v[224:225], off
	s_and_saveexec_b64 s[22:23], s[4:5]
	s_cbranch_execz .LBB0_167
	s_waitcnt lgkmcnt(0)
	v_add_f32_e32 v220, v220, v221
	v_cndmask_b32_e64 v220, 0, v220, s[6:7]
	global_store_dword v[88:89], v220, off
	s_branch .LBB0_167
